# GU GEMM: epilogue stores stay in flight across first K-tiles of next unit (relaxed counted vmcnt + early As11 restage)
# speedup vs baseline: 1.0047x; 1.0047x over previous
.LBB0_561:
	s_andn2_b64 vcc, exec, s[22:23]
	s_cbranch_vccnz .LBB0_630
	s_mov_b32 s98, 0
	v_mov_b32_e32 v0, v242
	s_load_dword s9, s[54:55], 0x0
	s_mov_b32 s11, s76
	v_mov_b32_e32 v12, v242
	s_waitcnt lgkmcnt(0)
	s_cmpk_gt_i32 s11, 0x15ff
	v_readfirstlane_b32 s3, v12
	s_cbranch_scc1 .LBB0_580
	v_lshlrev_b32_e32 v0, 4, v12
	v_add_u32_e32 v1, 0x2000, v0
	v_ashrrev_i32_e32 v2, 31, v1
	v_lshrrev_b32_e32 v2, 22, v2
	v_add_u32_e32 v2, v1, v2
	v_ashrrev_i32_e32 v2, 10, v2
	v_mul_i32_i24_e32 v3, 0x400, v2
	v_sub_u32_e32 v1, v1, v3
	v_lshrrev_b32_e32 v3, 4, v1
	v_bitop3_b32 v1, v3, v1, 32 bitop3:0x6c
	v_ashrrev_i32_e32 v3, 31, v1
	v_lshrrev_b32_e32 v3, 26, v3
	s_mul_i32 s0, s56, 0x1600000
	v_add_u32_e32 v3, v1, v3
	v_lshlrev_b32_e32 v5, 3, v2
	s_add_u32 s0, s84, s0
	v_ashrrev_i32_e32 v4, 6, v3
	v_and_b32_e32 v5, -16, v5
	v_and_b32_e32 v3, 0xc0, v3
	s_addc_u32 s2, s85, 0
	v_add_u32_e32 v7, v4, v5
	v_lshlrev_b32_e32 v2, 5, v2
	v_sub_u32_e32 v1, v1, v3
	s_add_u32 s17, s0, 0x980000
	v_and_b32_e32 v6, 3, v4
	s_mov_b32 s0, 0x1fffe0
	v_lshrrev_b32_e32 v8, 2, v7
	v_lshlrev_b32_e32 v9, 1, v7
	v_and_b32_e32 v2, 32, v2
	v_ashrrev_i16_sdwa v1, v243, sext(v1) dst_sel:DWORD dst_unused:UNUSED_PAD src0_sel:DWORD src1_sel:BYTE_0
	v_and_or_b32 v6, v7, s0, v6
	v_and_b32_e32 v8, 4, v8
	v_and_b32_e32 v9, 24, v9
	v_add_u32_sdwa v1, v2, sext(v1) dst_sel:DWORD dst_unused:UNUSED_PAD src0_sel:DWORD src1_sel:WORD_0
	v_or3_b32 v6, v6, v8, v9
	v_lshlrev_b32_e32 v2, 1, v1
	v_lshlrev_b32_e32 v1, 3, v1
	v_lshl_add_u32 v128, v6, 11, v2
	v_and_b32_e32 v6, 0x3ffff00, v1
	v_add_u32_e32 v1, v6, v7
	v_and_b32_e32 v7, 62, v2
	v_lshl_or_b32 v130, v1, 6, v7
	v_bfe_i32 v1, v12, 27, 1
	v_lshrrev_b32_e32 v1, 22, v1
	v_add_u32_e32 v1, v0, v1
	v_and_b32_e32 v1, 0xfffffc00, v1
	v_sub_u32_e32 v0, v0, v1
	v_lshrrev_b32_e32 v1, 4, v0
	v_ashrrev_i32_e32 v2, 31, v12
	v_bitop3_b32 v0, v1, v0, 32 bitop3:0x6c
	v_lshrrev_b32_e32 v2, 26, v2
	v_ashrrev_i32_e32 v1, 31, v0
	v_add_u32_e32 v2, v12, v2
	v_lshrrev_b32_e32 v1, 26, v1
	v_ashrrev_i32_e32 v2, 6, v2
	v_add_u32_e32 v1, v0, v1
	v_lshlrev_b32_e32 v3, 3, v2
	v_ashrrev_i32_e32 v8, 6, v1
	v_and_b32_e32 v9, -16, v3
	s_addc_u32 s18, s2, 0
	v_add_u32_e32 v3, v8, v9
	v_and_b32_e32 v10, 3, v8
	s_ashr_i32 s33, s11, 31
	v_and_or_b32 v10, v3, s0, v10
	s_lshr_b32 s0, s33, 29
	s_add_i32 s0, s11, s0
	s_ashr_i32 s25, s3, 6
	s_ashr_i32 s2, s0, 3
	s_and_b32 s0, s0, -8
	s_ashr_i32 s24, s3, 8
	s_lshl_b32 s19, s25, 10
	s_sub_i32 s0, s11, s0
	s_cmp_lt_i32 s0, 0
	s_movk_i32 s22, 0x2c1
	s_cselect_b32 s22, s22, 0x2c0
	s_mul_i32 s0, s0, s22
	s_add_i32 s0, s0, s2
	s_mul_hi_i32 s2, s0, 0x2e8ba2e9
	s_lshr_b32 s22, s2, 31
	s_ashr_i32 s2, s2, 5
	s_add_i32 s2, s2, s22
	s_lshl_b32 s22, s2, 3
	s_mulk_i32 s2, 0xb0
	s_sub_i32 s2, s0, s2
	s_bfe_u32 s0, s2, 0x3001c
	s_add_i32 s23, s2, s0
	s_sext_i32_i16 s0, s23
	s_and_b32 s23, s23, 0xfff8
	s_sub_i32 s2, s2, s23
	s_sext_i32_i16 s2, s2
	v_and_b32_e32 v1, 0xc0, v1
	s_lshr_b32 s0, s0, 3
	s_add_i32 s38, s22, s2
	v_lshlrev_b32_e32 v2, 5, v2
	v_sub_u32_e32 v0, v0, v1
	s_ashr_i32 s39, s38, 31
	s_bfe_i64 s[26:27], s[0:1], 0x100000
	v_lshrrev_b32_e32 v11, 2, v3
	v_lshlrev_b32_e32 v13, 1, v3
	v_and_b32_e32 v2, 32, v2
	v_ashrrev_i16_sdwa v0, v243, sext(v0) dst_sel:DWORD dst_unused:UNUSED_PAD src0_sel:DWORD src1_sel:BYTE_0
	s_lshl_b64 s[22:23], s[38:39], 19
	s_lshl_b64 s[26:27], s[26:27], 19
	v_and_b32_e32 v11, 4, v11
	v_and_b32_e32 v13, 24, v13
	v_add_u32_sdwa v0, v2, sext(v0) dst_sel:DWORD dst_unused:UNUSED_PAD src0_sel:DWORD src1_sel:WORD_0
	s_add_u32 s40, s17, s26
	v_or3_b32 v10, v10, v11, v13
	v_lshlrev_b32_e32 v1, 1, v0
	s_addc_u32 s41, s18, s27
	s_add_i32 s48, s19, 0
	v_lshl_add_u32 v132, v10, 11, v1
	s_add_i32 m0, s48, 0x10000
	v_lshlrev_b32_e32 v0, 3, v0
	global_load_lds_dwordx4 v132, s[40:41]
	s_add_i32 m0, s48, 0x12000
	s_add_u32 s26, s40, 0x40000
	global_load_lds_dwordx4 v128, s[40:41]
	s_addc_u32 s27, s41, 0
	s_add_i32 m0, s48, 0x14000
	v_and_b32_e32 v10, 0x3ffff00, v0
	global_load_lds_dwordx4 v132, s[26:27]
	s_add_i32 m0, s48, 0x16000
	s_add_u32 s42, s62, s22
	v_add_u32_e32 v0, v10, v3
	v_and_b32_e32 v11, 62, v1
	s_addc_u32 s43, s63, s23
	s_add_i32 s49, s48, 0x2000
	v_lshl_or_b32 v134, v0, 6, v11
	global_load_lds_dwordx4 v128, s[26:27]
	s_mov_b32 m0, s48
	s_add_u32 s22, s42, 0x2000
	global_load_lds_dwordx4 v134, s[42:43]
	s_mov_b32 m0, s49
	s_addc_u32 s23, s43, 0
	s_add_i32 s52, s48, 0x4000
	global_load_lds_dwordx4 v130, s[42:43]
	s_mov_b32 m0, s52
	s_add_i32 s53, s48, 0x6000
	global_load_lds_dwordx4 v134, s[22:23]
	s_mov_b32 m0, s53
	v_mov_b32_e32 v133, v209
	global_load_lds_dwordx4 v130, s[22:23]
	v_mov_b32_e32 v129, v209
	s_cmp_eq_u32 s24, 1
	s_mov_b64 s[70:71], s[54:55]
	s_mov_b32 s54, s56
	v_lshl_add_u64 v[0:1], s[40:41], 0, v[132:133]
	s_cselect_b64 s[22:23], -1, 0
	s_cmp_lg_u32 s24, 1
	v_lshl_add_u64 v[2:3], s[40:41], 0, v[128:129]
	s_cbranch_scc1 .LBB0_565
	s_barrier

.LBB0_571:
	s_add_u32 s44, s40, 0x6000
	s_addc_u32 s45, s41, 0
	s_and_b64 s[42:43], s[42:43], exec
	s_cselect_b32 s46, s29, s44
	s_cselect_b32 s47, s3, s45
	s_cselect_b32 s45, s27, s64
	s_cselect_b32 s44, s39, s61
	s_add_u32 s42, s46, 0x8000
	s_addc_u32 s43, s47, 0
	s_add_i32 s66, 0, 0x10000
	v_add_u32_e32 v169, s66, v159
	s_add_i32 s68, 0, 0x14000
	ds_read_b128 v[170:173], v169
	ds_read_b128 v[174:177], v169 offset:1024
	ds_read_b128 v[178:181], v169 offset:2048
	ds_read_b128 v[182:185], v169 offset:3072
	v_add_u32_e32 v169, s68, v159
	ds_read_b128 v[186:189], v169
	ds_read_b128 v[190:193], v169 offset:1024
	ds_read_b128 v[194:197], v169 offset:2048
	ds_read_b128 v[198:201], v169 offset:3072
	v_lshl_add_u64 v[206:207], s[40:41], 0, v[152:153]
	s_add_i32 m0, s48, 0xc000
	ds_read_b128 v[202:205], v160
	ds_read_b128 v[218:221], v160 offset:1024
	ds_read_b128 v[222:225], v160 offset:2048
	ds_read_b128 v[226:229], v160 offset:3072
	ds_read_b128 v[230:233], v160 offset:4096
	ds_read_b128 v[234:237], v160 offset:5120
	ds_read_b128 v[238:241], v160 offset:6144
	ds_read_b128 v[246:249], v160 offset:7168
	global_load_lds_dwordx4 v[206:207], off
	v_lshl_add_u64 v[206:207], s[40:41], 0, v[154:155]
	s_add_i32 m0, s48, 0xe000
	s_nop 0
	global_load_lds_dwordx4 v[206:207], off
	s_cmp_lg_u32 s98, 0
	s_cbranch_scc1 .Lgu_rlx0
	s_waitcnt vmcnt(8)
.Lgu_join0:
	s_waitcnt lgkmcnt(0)
	s_barrier
	s_setprio 1
	s_waitcnt lgkmcnt(0)
	v_mfma_f32_16x16x32_bf16 v[116:119], v[170:173], v[202:205], v[116:119]
	v_mfma_f32_16x16x32_bf16 v[124:127], v[178:181], v[202:205], v[124:127]
	v_mfma_f32_16x16x32_bf16 v[100:103], v[170:173], v[222:225], v[100:103]
	v_mfma_f32_16x16x32_bf16 v[108:111], v[178:181], v[222:225], v[108:111]
	v_mfma_f32_16x16x32_bf16 v[84:87], v[170:173], v[230:233], v[84:87]
	v_mfma_f32_16x16x32_bf16 v[92:95], v[178:181], v[230:233], v[92:95]
	v_mfma_f32_16x16x32_bf16 v[68:71], v[170:173], v[238:241], v[68:71]
	v_mfma_f32_16x16x32_bf16 v[76:79], v[178:181], v[238:241], v[76:79]
	v_mfma_f32_16x16x32_bf16 v[116:119], v[174:177], v[218:221], v[116:119]
	v_mfma_f32_16x16x32_bf16 v[124:127], v[182:185], v[218:221], v[124:127]
	v_mfma_f32_16x16x32_bf16 v[100:103], v[174:177], v[226:229], v[100:103]
	v_mfma_f32_16x16x32_bf16 v[108:111], v[182:185], v[226:229], v[108:111]
	v_mfma_f32_16x16x32_bf16 v[84:87], v[174:177], v[234:237], v[84:87]
	v_mfma_f32_16x16x32_bf16 v[92:95], v[182:185], v[234:237], v[92:95]
	v_mfma_f32_16x16x32_bf16 v[68:71], v[174:177], v[246:249], v[68:71]
	v_mfma_f32_16x16x32_bf16 v[76:79], v[182:185], v[246:249], v[76:79]
	s_setprio 0
	s_setprio 1
	v_mfma_f32_16x16x32_bf16 v[112:115], v[186:189], v[202:205], v[112:115]
	v_mfma_f32_16x16x32_bf16 v[120:123], v[194:197], v[202:205], v[120:123]
	v_mfma_f32_16x16x32_bf16 v[96:99], v[186:189], v[222:225], v[96:99]
	v_mfma_f32_16x16x32_bf16 v[104:107], v[194:197], v[222:225], v[104:107]
	v_mfma_f32_16x16x32_bf16 v[80:83], v[186:189], v[230:233], v[80:83]
	v_mfma_f32_16x16x32_bf16 v[88:91], v[194:197], v[230:233], v[88:91]
	v_mfma_f32_16x16x32_bf16 v[64:67], v[186:189], v[238:241], v[64:67]
	v_mfma_f32_16x16x32_bf16 v[72:75], v[194:197], v[238:241], v[72:75]
	v_mfma_f32_16x16x32_bf16 v[112:115], v[190:193], v[218:221], v[112:115]
	v_mfma_f32_16x16x32_bf16 v[120:123], v[198:201], v[218:221], v[120:123]
	v_mfma_f32_16x16x32_bf16 v[96:99], v[190:193], v[226:229], v[96:99]
	v_mfma_f32_16x16x32_bf16 v[104:107], v[198:201], v[226:229], v[104:107]
	v_mfma_f32_16x16x32_bf16 v[80:83], v[190:193], v[234:237], v[80:83]
	v_mfma_f32_16x16x32_bf16 v[88:91], v[198:201], v[234:237], v[88:91]
	v_mfma_f32_16x16x32_bf16 v[64:67], v[190:193], v[246:249], v[64:67]
	v_mfma_f32_16x16x32_bf16 v[72:75], v[198:201], v[246:249], v[72:75]
	s_setprio 0
	s_barrier
	s_add_i32 s66, s66, s19
	v_lshl_add_u64 v[206:207], s[44:45], 0, v[132:133]
	s_mov_b32 m0, s66
	ds_read_b128 v[202:205], v160 offset:16384
	ds_read_b128 v[218:221], v160 offset:17408
	ds_read_b128 v[222:225], v160 offset:18432
	ds_read_b128 v[226:229], v160 offset:19456
	ds_read_b128 v[230:233], v160 offset:20480
	ds_read_b128 v[234:237], v160 offset:21504
	ds_read_b128 v[238:241], v160 offset:22528
	ds_read_b128 v[246:249], v160 offset:23552
	global_load_lds_dwordx4 v[206:207], off
	s_add_i32 m0, s66, 0x2000
	s_add_u32 s66, s44, 0x40000
	v_lshl_add_u64 v[214:215], s[44:45], 0, v[128:129]
	s_addc_u32 s67, s45, 0
	s_add_i32 s68, s68, s19
	global_load_lds_dwordx4 v[214:215], off
	v_lshl_add_u64 v[216:217], s[66:67], 0, v[132:133]
	s_mov_b32 m0, s68
	s_nop 0
	global_load_lds_dwordx4 v[216:217], off
	v_lshl_add_u64 v[216:217], s[66:67], 0, v[128:129]
	s_add_i32 m0, s68, 0x2000
	s_nop 0
	global_load_lds_dwordx4 v[216:217], off
	v_lshl_add_u64 v[216:217], s[46:47], 0, v[134:135]
	s_mov_b32 m0, s48
	s_nop 0
	global_load_lds_dwordx4 v[216:217], off
	v_lshl_add_u64 v[216:217], s[46:47], 0, v[130:131]
	s_mov_b32 m0, s49
	s_nop 0
	global_load_lds_dwordx4 v[216:217], off
	s_cmp_lg_u32 s98, 0
	s_cbranch_scc1 .Lgu_rlx1
	s_waitcnt vmcnt(8)
.Lgu_join1:
	s_waitcnt lgkmcnt(0)
	s_barrier
	s_setprio 1
	s_waitcnt lgkmcnt(0)
	v_mfma_f32_16x16x32_bf16 v[52:55], v[170:173], v[202:205], v[52:55]
	v_mfma_f32_16x16x32_bf16 v[60:63], v[178:181], v[202:205], v[60:63]
	v_mfma_f32_16x16x32_bf16 v[36:39], v[170:173], v[222:225], v[36:39]
	v_mfma_f32_16x16x32_bf16 v[44:47], v[178:181], v[222:225], v[44:47]
	v_mfma_f32_16x16x32_bf16 v[20:23], v[170:173], v[230:233], v[20:23]
	v_mfma_f32_16x16x32_bf16 v[28:31], v[178:181], v[230:233], v[28:31]
	v_mfma_f32_16x16x32_bf16 v[4:7], v[170:173], v[238:241], v[4:7]
	v_mfma_f32_16x16x32_bf16 v[12:15], v[178:181], v[238:241], v[12:15]
	v_mfma_f32_16x16x32_bf16 v[52:55], v[174:177], v[218:221], v[52:55]
	v_mfma_f32_16x16x32_bf16 v[60:63], v[182:185], v[218:221], v[60:63]
	v_mfma_f32_16x16x32_bf16 v[36:39], v[174:177], v[226:229], v[36:39]
	v_mfma_f32_16x16x32_bf16 v[44:47], v[182:185], v[226:229], v[44:47]
	v_mfma_f32_16x16x32_bf16 v[20:23], v[174:177], v[234:237], v[20:23]
	v_mfma_f32_16x16x32_bf16 v[28:31], v[182:185], v[234:237], v[28:31]
	v_mfma_f32_16x16x32_bf16 v[4:7], v[174:177], v[246:249], v[4:7]
	v_mfma_f32_16x16x32_bf16 v[12:15], v[182:185], v[246:249], v[12:15]
	s_setprio 0
	s_setprio 1
	v_mfma_f32_16x16x32_bf16 v[48:51], v[186:189], v[202:205], v[48:51]
	v_mfma_f32_16x16x32_bf16 v[56:59], v[194:197], v[202:205], v[56:59]
	v_mfma_f32_16x16x32_bf16 v[32:35], v[186:189], v[222:225], v[32:35]
	v_mfma_f32_16x16x32_bf16 v[40:43], v[194:197], v[222:225], v[40:43]
	v_mfma_f32_16x16x32_bf16 v[16:19], v[186:189], v[230:233], v[16:19]
	v_mfma_f32_16x16x32_bf16 v[24:27], v[194:197], v[230:233], v[24:27]
	v_mfma_f32_16x16x32_bf16 v[0:3], v[186:189], v[238:241], v[0:3]
	v_mfma_f32_16x16x32_bf16 v[8:11], v[194:197], v[238:241], v[8:11]
	v_mfma_f32_16x16x32_bf16 v[48:51], v[190:193], v[218:221], v[48:51]
	v_mfma_f32_16x16x32_bf16 v[56:59], v[198:201], v[218:221], v[56:59]
	v_mfma_f32_16x16x32_bf16 v[32:35], v[190:193], v[226:229], v[32:35]
	v_mfma_f32_16x16x32_bf16 v[40:43], v[198:201], v[226:229], v[40:43]
	v_mfma_f32_16x16x32_bf16 v[16:19], v[190:193], v[234:237], v[16:19]
	v_mfma_f32_16x16x32_bf16 v[24:27], v[198:201], v[234:237], v[24:27]
	v_mfma_f32_16x16x32_bf16 v[0:3], v[190:193], v[246:249], v[0:3]
	v_mfma_f32_16x16x32_bf16 v[8:11], v[198:201], v[246:249], v[8:11]
	s_setprio 0
	s_barrier
	s_add_i32 s66, 0, 0x18000
	v_add_u32_e32 v169, s66, v159
	s_add_i32 s67, 0, 0x1c000
	ds_read_b128 v[170:173], v169
	ds_read_b128 v[174:177], v169 offset:1024
	ds_read_b128 v[178:181], v169 offset:2048
	ds_read_b128 v[182:185], v169 offset:3072
	v_add_u32_e32 v169, s67, v159
	ds_read_b128 v[186:189], v169
	ds_read_b128 v[190:193], v169 offset:1024
	ds_read_b128 v[194:197], v169 offset:2048
	ds_read_b128 v[198:201], v169 offset:3072
	s_add_u32 s46, s46, 0x2000
	s_addc_u32 s47, s47, 0
	s_mov_b32 m0, s52
	v_lshl_add_u64 v[216:217], s[46:47], 0, v[134:135]
	ds_read_b128 v[202:205], v160 offset:32768
	ds_read_b128 v[218:221], v160 offset:33792
	ds_read_b128 v[222:225], v160 offset:34816
	ds_read_b128 v[226:229], v160 offset:35840
	ds_read_b128 v[230:233], v160 offset:36864
	ds_read_b128 v[234:237], v160 offset:37888
	ds_read_b128 v[238:241], v160 offset:38912
	ds_read_b128 v[246:249], v160 offset:39936
	global_load_lds_dwordx4 v[216:217], off
	v_lshl_add_u64 v[216:217], s[46:47], 0, v[130:131]
	s_mov_b32 m0, s53
	s_nop 0
	global_load_lds_dwordx4 v[216:217], off
	s_cmp_lg_u32 s98, 0
	s_cbranch_scc1 .Lgu_rlx2
	s_waitcnt vmcnt(8)
.Lgu_join2:
	s_waitcnt lgkmcnt(0)
	s_barrier
	s_setprio 1
	s_waitcnt lgkmcnt(0)
	v_mfma_f32_16x16x32_bf16 v[116:119], v[170:173], v[202:205], v[116:119]
	v_mfma_f32_16x16x32_bf16 v[124:127], v[178:181], v[202:205], v[124:127]
	v_mfma_f32_16x16x32_bf16 v[100:103], v[170:173], v[222:225], v[100:103]
	v_mfma_f32_16x16x32_bf16 v[108:111], v[178:181], v[222:225], v[108:111]
	v_mfma_f32_16x16x32_bf16 v[84:87], v[170:173], v[230:233], v[84:87]
	v_mfma_f32_16x16x32_bf16 v[92:95], v[178:181], v[230:233], v[92:95]
	v_mfma_f32_16x16x32_bf16 v[68:71], v[170:173], v[238:241], v[68:71]
	v_mfma_f32_16x16x32_bf16 v[76:79], v[178:181], v[238:241], v[76:79]
	v_mfma_f32_16x16x32_bf16 v[116:119], v[174:177], v[218:221], v[116:119]
	v_mfma_f32_16x16x32_bf16 v[124:127], v[182:185], v[218:221], v[124:127]
	v_mfma_f32_16x16x32_bf16 v[100:103], v[174:177], v[226:229], v[100:103]
	v_mfma_f32_16x16x32_bf16 v[108:111], v[182:185], v[226:229], v[108:111]
	v_mfma_f32_16x16x32_bf16 v[84:87], v[174:177], v[234:237], v[84:87]
	v_mfma_f32_16x16x32_bf16 v[92:95], v[182:185], v[234:237], v[92:95]
	v_mfma_f32_16x16x32_bf16 v[68:71], v[174:177], v[246:249], v[68:71]
	v_mfma_f32_16x16x32_bf16 v[76:79], v[182:185], v[246:249], v[76:79]
	s_setprio 0
	s_setprio 1
	v_mfma_f32_16x16x32_bf16 v[112:115], v[186:189], v[202:205], v[112:115]
	v_mfma_f32_16x16x32_bf16 v[120:123], v[194:197], v[202:205], v[120:123]
	v_mfma_f32_16x16x32_bf16 v[96:99], v[186:189], v[222:225], v[96:99]
	v_mfma_f32_16x16x32_bf16 v[104:107], v[194:197], v[222:225], v[104:107]
	v_mfma_f32_16x16x32_bf16 v[80:83], v[186:189], v[230:233], v[80:83]
	v_mfma_f32_16x16x32_bf16 v[88:91], v[194:197], v[230:233], v[88:91]
	v_mfma_f32_16x16x32_bf16 v[64:67], v[186:189], v[238:241], v[64:67]
	v_mfma_f32_16x16x32_bf16 v[72:75], v[194:197], v[238:241], v[72:75]
	v_mfma_f32_16x16x32_bf16 v[112:115], v[190:193], v[218:221], v[112:115]
	v_mfma_f32_16x16x32_bf16 v[120:123], v[198:201], v[218:221], v[120:123]
	v_mfma_f32_16x16x32_bf16 v[96:99], v[190:193], v[226:229], v[96:99]
	v_mfma_f32_16x16x32_bf16 v[104:107], v[198:201], v[226:229], v[104:107]
	v_mfma_f32_16x16x32_bf16 v[80:83], v[190:193], v[234:237], v[80:83]
	v_mfma_f32_16x16x32_bf16 v[88:91], v[198:201], v[234:237], v[88:91]
	v_mfma_f32_16x16x32_bf16 v[64:67], v[190:193], v[246:249], v[64:67]
	v_mfma_f32_16x16x32_bf16 v[72:75], v[198:201], v[246:249], v[72:75]
	s_setprio 0
	s_barrier
	s_add_i32 s46, s66, s19
	v_lshl_add_u64 v[206:207], v[206:207], 0, s[4:5]
	s_mov_b32 m0, s46
	ds_read_b128 v[202:205], v160 offset:49152
	ds_read_b128 v[218:221], v160 offset:50176
	ds_read_b128 v[222:225], v160 offset:51200
	ds_read_b128 v[226:229], v160 offset:52224
	ds_read_b128 v[230:233], v160 offset:53248
	ds_read_b128 v[234:237], v160 offset:54272
	ds_read_b128 v[238:241], v160 offset:55296
	ds_read_b128 v[246:249], v160 offset:56320
	global_load_lds_dwordx4 v[206:207], off
	s_add_i32 m0, s46, 0x2000
	s_add_u32 s44, s44, 0x40080
	v_lshl_add_u64 v[206:207], v[214:215], 0, s[4:5]
	s_addc_u32 s45, s45, 0
	s_add_i32 s46, s67, s19
	global_load_lds_dwordx4 v[206:207], off
	v_lshl_add_u64 v[206:207], s[44:45], 0, v[132:133]
	s_mov_b32 m0, s46
	s_nop 0
	global_load_lds_dwordx4 v[206:207], off
	v_lshl_add_u64 v[206:207], s[44:45], 0, v[128:129]
	s_add_i32 m0, s46, 0x2000
	s_nop 0
	global_load_lds_dwordx4 v[206:207], off
	v_lshl_add_u64 v[206:207], s[42:43], 0, v[134:135]
	s_mov_b32 m0, s0
	s_nop 0
	global_load_lds_dwordx4 v[206:207], off
	v_lshl_add_u64 v[206:207], s[42:43], 0, v[130:131]
	s_mov_b32 m0, s56
	s_nop 0
	global_load_lds_dwordx4 v[206:207], off
	s_waitcnt vmcnt(8)
	s_mov_b32 s98, 0
	s_waitcnt lgkmcnt(0)
	s_barrier
	s_setprio 1
	s_waitcnt lgkmcnt(0)
	v_mfma_f32_16x16x32_bf16 v[52:55], v[170:173], v[202:205], v[52:55]
	v_mfma_f32_16x16x32_bf16 v[60:63], v[178:181], v[202:205], v[60:63]
	v_mfma_f32_16x16x32_bf16 v[36:39], v[170:173], v[222:225], v[36:39]
	v_mfma_f32_16x16x32_bf16 v[44:47], v[178:181], v[222:225], v[44:47]
	v_mfma_f32_16x16x32_bf16 v[20:23], v[170:173], v[230:233], v[20:23]
	v_mfma_f32_16x16x32_bf16 v[28:31], v[178:181], v[230:233], v[28:31]
	v_mfma_f32_16x16x32_bf16 v[4:7], v[170:173], v[238:241], v[4:7]
	v_mfma_f32_16x16x32_bf16 v[12:15], v[178:181], v[238:241], v[12:15]
	v_mfma_f32_16x16x32_bf16 v[52:55], v[174:177], v[218:221], v[52:55]
	v_mfma_f32_16x16x32_bf16 v[60:63], v[182:185], v[218:221], v[60:63]
	v_mfma_f32_16x16x32_bf16 v[36:39], v[174:177], v[226:229], v[36:39]
	v_mfma_f32_16x16x32_bf16 v[44:47], v[182:185], v[226:229], v[44:47]
	v_mfma_f32_16x16x32_bf16 v[20:23], v[174:177], v[234:237], v[20:23]
	v_mfma_f32_16x16x32_bf16 v[28:31], v[182:185], v[234:237], v[28:31]
	v_mfma_f32_16x16x32_bf16 v[4:7], v[174:177], v[246:249], v[4:7]
	v_mfma_f32_16x16x32_bf16 v[12:15], v[182:185], v[246:249], v[12:15]
	s_setprio 0
	s_setprio 1
	v_mfma_f32_16x16x32_bf16 v[48:51], v[186:189], v[202:205], v[48:51]
	v_mfma_f32_16x16x32_bf16 v[56:59], v[194:197], v[202:205], v[56:59]
	v_mfma_f32_16x16x32_bf16 v[32:35], v[186:189], v[222:225], v[32:35]
	v_mfma_f32_16x16x32_bf16 v[40:43], v[194:197], v[222:225], v[40:43]
	v_mfma_f32_16x16x32_bf16 v[16:19], v[186:189], v[230:233], v[16:19]
	v_mfma_f32_16x16x32_bf16 v[24:27], v[194:197], v[230:233], v[24:27]
	v_mfma_f32_16x16x32_bf16 v[0:3], v[186:189], v[238:241], v[0:3]
	v_mfma_f32_16x16x32_bf16 v[8:11], v[194:197], v[238:241], v[8:11]
	v_mfma_f32_16x16x32_bf16 v[48:51], v[190:193], v[218:221], v[48:51]
	v_mfma_f32_16x16x32_bf16 v[56:59], v[198:201], v[218:221], v[56:59]
	v_mfma_f32_16x16x32_bf16 v[32:35], v[190:193], v[226:229], v[32:35]
	v_mfma_f32_16x16x32_bf16 v[40:43], v[198:201], v[226:229], v[40:43]
	v_mfma_f32_16x16x32_bf16 v[16:19], v[190:193], v[234:237], v[16:19]
	v_mfma_f32_16x16x32_bf16 v[24:27], v[198:201], v[234:237], v[24:27]
	v_mfma_f32_16x16x32_bf16 v[0:3], v[190:193], v[246:249], v[0:3]
	v_mfma_f32_16x16x32_bf16 v[8:11], v[198:201], v[246:249], v[8:11]
	s_setprio 0
	s_barrier
	s_add_i32 s65, s65, 2
	s_add_u32 s61, s61, 0x100
	s_addc_u32 s64, s64, 0
	s_add_u32 s40, s40, 0x10000
	s_addc_u32 s41, s41, 0
	s_cmp_gt_u32 s65, 13
	s_cbranch_scc1 .LBB0_574

.LBB0_576:
	s_add_u32 s100, s29, 0xa000
	s_addc_u32 s101, s3, 0
	v_lshl_add_u64 v[206:207], s[100:101], 0, v[152:153]
	s_add_i32 m0, s48, 0xc000
	s_nop 0
	global_load_lds_dwordx4 v[206:207], off
	v_lshl_add_u64 v[206:207], s[100:101], 0, v[154:155]
	s_add_i32 m0, s48, 0xe000
	s_nop 0
	global_load_lds_dwordx4 v[206:207], off
	s_waitcnt vmcnt(10)
	v_mul_f32_e32 v170, 0xbfb8aa3b, v168
	v_pk_mul_f32 v[176:177], v[170:171], v[116:117] op_sel_hi:[0,1]
	v_exp_f32_e32 v169, v176
	v_pk_mul_f32 v[120:121], v[124:125], v[120:121]
	v_pk_mul_f32 v[124:125], v[170:171], v[124:125] op_sel_hi:[0,1]
	v_pk_mul_f32 v[122:123], v[126:127], v[122:123]
	v_pk_mul_f32 v[174:175], v[170:171], v[118:119] op_sel_hi:[0,1]
	v_pk_mul_f32 v[126:127], v[170:171], v[126:127] op_sel_hi:[0,1]
	v_exp_f32_e32 v170, v124
	v_add_f32_e32 v124, 1.0, v169
	v_exp_f32_e32 v169, v177
	v_exp_f32_e32 v171, v125
	v_exp_f32_e32 v173, v126
	s_mul_i32 s3, s38, 22
	v_add_f32_e32 v125, 1.0, v169
	v_exp_f32_e32 v169, v174
	s_add_i32 s2, s3, s2
	s_ashr_i32 s3, s2, 31
	v_rcp_f32_e32 v124, v124
	v_add_f32_e32 v126, 1.0, v169
	v_exp_f32_e32 v169, v175
	v_exp_f32_e32 v175, v127
	v_add_f32_e32 v170, 1.0, v170
	v_rcp_f32_e32 v125, v125
	v_add_f32_e32 v127, 1.0, v169
	v_add_f32_e32 v171, 1.0, v171
	v_rcp_f32_e32 v126, v126
	v_rcp_f32_e32 v127, v127
	s_lshl_b64 s[2:3], s[2:3], 16
	v_rcp_f32_e32 v170, v170
	v_rcp_f32_e32 v171, v171
	v_add_f32_e32 v173, 1.0, v173
	v_add_f32_e32 v169, 1.0, v175
	s_add_u32 s38, s50, s2
	v_mul_f32_e32 v172, v168, v168
	v_rcp_f32_e32 v174, v173
	v_rcp_f32_e32 v175, v169
	v_pk_mul_f32 v[114:115], v[118:119], v[114:115]
	v_pk_mul_f32 v[112:113], v[116:117], v[112:113]
	s_addc_u32 s39, s51, s3
	v_pk_mul_f32 v[112:113], v[172:173], v[112:113] op_sel_hi:[0,1]
	v_pk_mul_f32 v[114:115], v[172:173], v[114:115] op_sel_hi:[0,1]
	v_lshl_add_u64 v[156:157], s[38:39], 0, v[136:137]
	v_pk_mul_f32 v[116:117], v[172:173], v[120:121] op_sel_hi:[0,1]
	v_pk_mul_f32 v[114:115], v[126:127], v[114:115]
	v_pk_mul_f32 v[112:113], v[124:125], v[112:113]
	v_lshl_add_u64 v[156:157], v[156:157], 0, v[208:209]
	v_pk_mul_f32 v[118:119], v[172:173], v[122:123] op_sel_hi:[0,1]
	v_pk_mul_f32 v[116:117], v[170:171], v[116:117]
	v_cvt_pk_bf16_f32 v112, v112, v113
	v_cvt_pk_bf16_f32 v113, v114, v115
	v_pk_mul_f32 v[118:119], v[174:175], v[118:119]
	v_cvt_pk_bf16_f32 v114, v116, v117
	v_pk_mul_f32 v[104:105], v[108:109], v[104:105]
	v_cvt_pk_bf16_f32 v115, v118, v119
	global_store_dwordx4 v[156:157], v[112:115], off nt
	v_pk_mul_f32 v[106:107], v[110:111], v[106:107]
	v_mul_f32_e32 v116, v167, v167
	v_mul_f32_e32 v114, 0xbfb8aa3b, v167
	v_pk_mul_f32 v[120:121], v[114:115], v[100:101] op_sel_hi:[0,1]
	v_pk_mul_f32 v[118:119], v[114:115], v[102:103] op_sel_hi:[0,1]
	v_exp_f32_e32 v115, v120
	v_exp_f32_e32 v118, v118
	v_exp_f32_e32 v119, v119
	v_pk_mul_f32 v[98:99], v[102:103], v[98:99]
	v_pk_mul_f32 v[108:109], v[114:115], v[108:109] op_sel_hi:[0,1]
	v_pk_mul_f32 v[110:111], v[114:115], v[110:111] op_sel_hi:[0,1]
	v_exp_f32_e32 v114, v108
	v_add_f32_e32 v108, 1.0, v115
	v_exp_f32_e32 v115, v121
	v_exp_f32_e32 v117, v109
	v_exp_f32_e32 v120, v111
	v_add_f32_e32 v111, 1.0, v119
	v_add_f32_e32 v109, 1.0, v115
	v_add_f32_e32 v115, 1.0, v117
	v_exp_f32_e32 v117, v110
	v_add_f32_e32 v110, 1.0, v118
	v_rcp_f32_e32 v108, v108
	v_add_f32_e32 v114, 1.0, v114
	v_rcp_f32_e32 v109, v109
	v_rcp_f32_e32 v110, v110
	v_add_f32_e32 v117, 1.0, v117
	v_rcp_f32_e32 v111, v111
	v_rcp_f32_e32 v114, v114
	v_rcp_f32_e32 v115, v115
	v_rcp_f32_e32 v118, v117
	v_add_f32_e32 v117, 1.0, v120
	v_rcp_f32_e32 v119, v117
	v_pk_mul_f32 v[96:97], v[100:101], v[96:97]
	v_pk_mul_f32 v[98:99], v[116:117], v[98:99] op_sel_hi:[0,1]
	v_pk_mul_f32 v[96:97], v[116:117], v[96:97] op_sel_hi:[0,1]
	v_lshl_add_u64 v[112:113], s[38:39], 0, v[138:139]
	v_pk_mul_f32 v[100:101], v[116:117], v[104:105] op_sel_hi:[0,1]
	v_pk_mul_f32 v[98:99], v[110:111], v[98:99]
	v_pk_mul_f32 v[96:97], v[108:109], v[96:97]
	v_lshl_add_u64 v[112:113], v[112:113], 0, v[208:209]
	v_pk_mul_f32 v[102:103], v[116:117], v[106:107] op_sel_hi:[0,1]
	v_pk_mul_f32 v[100:101], v[114:115], v[100:101]
	v_cvt_pk_bf16_f32 v96, v96, v97
	v_cvt_pk_bf16_f32 v97, v98, v99
	v_pk_mul_f32 v[102:103], v[118:119], v[102:103]
	v_cvt_pk_bf16_f32 v98, v100, v101
	v_pk_mul_f32 v[88:89], v[92:93], v[88:89]
	v_cvt_pk_bf16_f32 v99, v102, v103
	global_store_dwordx4 v[112:113], v[96:99], off nt
	v_pk_mul_f32 v[90:91], v[94:95], v[90:91]
	v_mul_f32_e32 v100, v166, v166
	v_mul_f32_e32 v98, 0xbfb8aa3b, v166
	v_pk_mul_f32 v[104:105], v[98:99], v[84:85] op_sel_hi:[0,1]
	v_pk_mul_f32 v[102:103], v[98:99], v[86:87] op_sel_hi:[0,1]
	v_exp_f32_e32 v99, v104
	v_exp_f32_e32 v102, v102
	v_exp_f32_e32 v103, v103
	v_pk_mul_f32 v[82:83], v[86:87], v[82:83]
	v_pk_mul_f32 v[92:93], v[98:99], v[92:93] op_sel_hi:[0,1]
	v_pk_mul_f32 v[94:95], v[98:99], v[94:95] op_sel_hi:[0,1]
	v_exp_f32_e32 v98, v92
	v_add_f32_e32 v92, 1.0, v99
	v_exp_f32_e32 v99, v105
	v_exp_f32_e32 v101, v93
	v_exp_f32_e32 v104, v95
	v_add_f32_e32 v95, 1.0, v103
	v_add_f32_e32 v93, 1.0, v99
	v_add_f32_e32 v99, 1.0, v101
	v_exp_f32_e32 v101, v94
	v_add_f32_e32 v94, 1.0, v102
	v_rcp_f32_e32 v92, v92
	v_add_f32_e32 v98, 1.0, v98
	v_rcp_f32_e32 v93, v93
	v_rcp_f32_e32 v94, v94
	v_add_f32_e32 v101, 1.0, v101
	v_rcp_f32_e32 v95, v95
	v_rcp_f32_e32 v98, v98
	v_rcp_f32_e32 v99, v99
	v_rcp_f32_e32 v102, v101
	v_add_f32_e32 v101, 1.0, v104
	v_rcp_f32_e32 v103, v101
	v_pk_mul_f32 v[80:81], v[84:85], v[80:81]
	v_pk_mul_f32 v[82:83], v[100:101], v[82:83] op_sel_hi:[0,1]
	v_pk_mul_f32 v[80:81], v[100:101], v[80:81] op_sel_hi:[0,1]
	v_lshl_add_u64 v[96:97], s[38:39], 0, v[140:141]
	v_pk_mul_f32 v[84:85], v[100:101], v[88:89] op_sel_hi:[0,1]
	v_pk_mul_f32 v[82:83], v[94:95], v[82:83]
	v_pk_mul_f32 v[80:81], v[92:93], v[80:81]
	v_lshl_add_u64 v[96:97], v[96:97], 0, v[208:209]
	v_pk_mul_f32 v[86:87], v[100:101], v[90:91] op_sel_hi:[0,1]
	v_pk_mul_f32 v[84:85], v[98:99], v[84:85]
	v_cvt_pk_bf16_f32 v80, v80, v81
	v_cvt_pk_bf16_f32 v81, v82, v83
	v_pk_mul_f32 v[86:87], v[102:103], v[86:87]
	v_cvt_pk_bf16_f32 v82, v84, v85
	v_pk_mul_f32 v[72:73], v[76:77], v[72:73]
	v_cvt_pk_bf16_f32 v83, v86, v87
	global_store_dwordx4 v[96:97], v[80:83], off nt
	v_pk_mul_f32 v[74:75], v[78:79], v[74:75]
	v_mul_f32_e32 v84, v165, v165
	v_mul_f32_e32 v82, 0xbfb8aa3b, v165
	v_pk_mul_f32 v[88:89], v[82:83], v[68:69] op_sel_hi:[0,1]
	v_pk_mul_f32 v[86:87], v[82:83], v[70:71] op_sel_hi:[0,1]
	v_exp_f32_e32 v83, v88
	v_exp_f32_e32 v86, v86
	v_exp_f32_e32 v87, v87
	v_pk_mul_f32 v[66:67], v[70:71], v[66:67]
	v_pk_mul_f32 v[76:77], v[82:83], v[76:77] op_sel_hi:[0,1]
	v_pk_mul_f32 v[78:79], v[82:83], v[78:79] op_sel_hi:[0,1]
	v_exp_f32_e32 v82, v76
	v_add_f32_e32 v76, 1.0, v83
	v_exp_f32_e32 v83, v89
	v_exp_f32_e32 v85, v77
	v_exp_f32_e32 v88, v79
	v_add_f32_e32 v79, 1.0, v87
	v_add_f32_e32 v77, 1.0, v83
	v_add_f32_e32 v83, 1.0, v85
	v_exp_f32_e32 v85, v78
	v_add_f32_e32 v78, 1.0, v86
	v_rcp_f32_e32 v76, v76
	v_add_f32_e32 v82, 1.0, v82
	v_rcp_f32_e32 v77, v77
	v_rcp_f32_e32 v78, v78
	v_add_f32_e32 v85, 1.0, v85
	v_rcp_f32_e32 v79, v79
	v_rcp_f32_e32 v82, v82
	v_rcp_f32_e32 v83, v83
	v_rcp_f32_e32 v86, v85
	v_add_f32_e32 v85, 1.0, v88
	v_rcp_f32_e32 v87, v85
	v_pk_mul_f32 v[64:65], v[68:69], v[64:65]
	v_pk_mul_f32 v[66:67], v[84:85], v[66:67] op_sel_hi:[0,1]
	v_pk_mul_f32 v[64:65], v[84:85], v[64:65] op_sel_hi:[0,1]
	v_lshl_add_u64 v[80:81], s[38:39], 0, v[142:143]
	v_pk_mul_f32 v[68:69], v[84:85], v[72:73] op_sel_hi:[0,1]
	v_pk_mul_f32 v[66:67], v[78:79], v[66:67]
	v_pk_mul_f32 v[64:65], v[76:77], v[64:65]
	v_lshl_add_u64 v[80:81], v[80:81], 0, v[208:209]
	v_pk_mul_f32 v[70:71], v[84:85], v[74:75] op_sel_hi:[0,1]
	v_pk_mul_f32 v[68:69], v[82:83], v[68:69]
	v_cvt_pk_bf16_f32 v64, v64, v65
	v_cvt_pk_bf16_f32 v65, v66, v67
	v_pk_mul_f32 v[70:71], v[86:87], v[70:71]
	v_cvt_pk_bf16_f32 v66, v68, v69
	v_pk_mul_f32 v[56:57], v[60:61], v[56:57]
	v_cvt_pk_bf16_f32 v67, v70, v71
	global_store_dwordx4 v[80:81], v[64:67], off nt
	v_pk_mul_f32 v[58:59], v[62:63], v[58:59]
	v_mul_f32_e32 v68, v164, v164
	v_mul_f32_e32 v66, 0xbfb8aa3b, v164
	v_pk_mul_f32 v[72:73], v[66:67], v[52:53] op_sel_hi:[0,1]
	v_pk_mul_f32 v[70:71], v[66:67], v[54:55] op_sel_hi:[0,1]
	v_exp_f32_e32 v67, v72
	v_exp_f32_e32 v70, v70
	v_exp_f32_e32 v71, v71
	v_pk_mul_f32 v[50:51], v[54:55], v[50:51]
	v_pk_mul_f32 v[60:61], v[66:67], v[60:61] op_sel_hi:[0,1]
	v_pk_mul_f32 v[62:63], v[66:67], v[62:63] op_sel_hi:[0,1]
	v_exp_f32_e32 v66, v60
	v_add_f32_e32 v60, 1.0, v67
	v_exp_f32_e32 v67, v73
	v_exp_f32_e32 v69, v61
	v_exp_f32_e32 v72, v63
	v_add_f32_e32 v63, 1.0, v71
	v_add_f32_e32 v61, 1.0, v67
	v_add_f32_e32 v67, 1.0, v69
	v_exp_f32_e32 v69, v62
	v_add_f32_e32 v62, 1.0, v70
	v_rcp_f32_e32 v60, v60
	v_add_f32_e32 v66, 1.0, v66
	v_rcp_f32_e32 v61, v61
	v_rcp_f32_e32 v62, v62
	v_add_f32_e32 v69, 1.0, v69
	v_rcp_f32_e32 v63, v63
	v_rcp_f32_e32 v66, v66
	v_rcp_f32_e32 v67, v67
	v_rcp_f32_e32 v70, v69
	v_add_f32_e32 v69, 1.0, v72
	v_rcp_f32_e32 v71, v69
	v_pk_mul_f32 v[48:49], v[52:53], v[48:49]
	v_pk_mul_f32 v[50:51], v[68:69], v[50:51] op_sel_hi:[0,1]
	v_pk_mul_f32 v[48:49], v[68:69], v[48:49] op_sel_hi:[0,1]
	v_lshl_add_u64 v[64:65], s[38:39], 0, v[144:145]
	v_pk_mul_f32 v[52:53], v[68:69], v[56:57] op_sel_hi:[0,1]
	v_pk_mul_f32 v[50:51], v[62:63], v[50:51]
	v_pk_mul_f32 v[48:49], v[60:61], v[48:49]
	v_lshl_add_u64 v[64:65], v[64:65], 0, v[208:209]
	v_pk_mul_f32 v[54:55], v[68:69], v[58:59] op_sel_hi:[0,1]
	v_pk_mul_f32 v[52:53], v[66:67], v[52:53]
	v_cvt_pk_bf16_f32 v48, v48, v49
	v_cvt_pk_bf16_f32 v49, v50, v51
	v_pk_mul_f32 v[54:55], v[70:71], v[54:55]
	v_cvt_pk_bf16_f32 v50, v52, v53
	v_pk_mul_f32 v[40:41], v[44:45], v[40:41]
	v_cvt_pk_bf16_f32 v51, v54, v55
	global_store_dwordx4 v[64:65], v[48:51], off nt
	v_pk_mul_f32 v[42:43], v[46:47], v[42:43]
	v_mul_f32_e32 v52, v163, v163
	v_mul_f32_e32 v50, 0xbfb8aa3b, v163
	v_pk_mul_f32 v[56:57], v[50:51], v[36:37] op_sel_hi:[0,1]
	v_pk_mul_f32 v[54:55], v[50:51], v[38:39] op_sel_hi:[0,1]
	v_exp_f32_e32 v51, v56
	v_exp_f32_e32 v54, v54
	v_exp_f32_e32 v55, v55
	v_pk_mul_f32 v[34:35], v[38:39], v[34:35]
	v_pk_mul_f32 v[44:45], v[50:51], v[44:45] op_sel_hi:[0,1]
	v_pk_mul_f32 v[46:47], v[50:51], v[46:47] op_sel_hi:[0,1]
	v_exp_f32_e32 v50, v44
	v_add_f32_e32 v44, 1.0, v51
	v_exp_f32_e32 v51, v57
	v_exp_f32_e32 v53, v45
	v_exp_f32_e32 v56, v47
	v_add_f32_e32 v47, 1.0, v55
	v_add_f32_e32 v45, 1.0, v51
	v_add_f32_e32 v51, 1.0, v53
	v_exp_f32_e32 v53, v46
	v_add_f32_e32 v46, 1.0, v54
	v_rcp_f32_e32 v44, v44
	v_add_f32_e32 v50, 1.0, v50
	v_rcp_f32_e32 v45, v45
	v_rcp_f32_e32 v46, v46
	v_add_f32_e32 v53, 1.0, v53
	v_rcp_f32_e32 v47, v47
	v_rcp_f32_e32 v50, v50
	v_rcp_f32_e32 v51, v51
	v_rcp_f32_e32 v54, v53
	v_add_f32_e32 v53, 1.0, v56
	v_rcp_f32_e32 v55, v53
	v_pk_mul_f32 v[32:33], v[36:37], v[32:33]
	v_pk_mul_f32 v[34:35], v[52:53], v[34:35] op_sel_hi:[0,1]
	v_pk_mul_f32 v[32:33], v[52:53], v[32:33] op_sel_hi:[0,1]
	v_lshl_add_u64 v[48:49], s[38:39], 0, v[146:147]
	v_pk_mul_f32 v[36:37], v[52:53], v[40:41] op_sel_hi:[0,1]
	v_pk_mul_f32 v[34:35], v[46:47], v[34:35]
	v_pk_mul_f32 v[32:33], v[44:45], v[32:33]
	v_lshl_add_u64 v[48:49], v[48:49], 0, v[208:209]
	v_pk_mul_f32 v[38:39], v[52:53], v[42:43] op_sel_hi:[0,1]
	v_pk_mul_f32 v[36:37], v[50:51], v[36:37]
	v_cvt_pk_bf16_f32 v32, v32, v33
	v_cvt_pk_bf16_f32 v33, v34, v35
	v_pk_mul_f32 v[38:39], v[54:55], v[38:39]
	v_cvt_pk_bf16_f32 v34, v36, v37
	v_pk_mul_f32 v[24:25], v[28:29], v[24:25]
	v_cvt_pk_bf16_f32 v35, v38, v39
	global_store_dwordx4 v[48:49], v[32:35], off nt
	v_pk_mul_f32 v[26:27], v[30:31], v[26:27]
	v_mul_f32_e32 v36, v162, v162
	v_mul_f32_e32 v34, 0xbfb8aa3b, v162
	v_pk_mul_f32 v[40:41], v[34:35], v[20:21] op_sel_hi:[0,1]
	v_pk_mul_f32 v[38:39], v[34:35], v[22:23] op_sel_hi:[0,1]
	v_exp_f32_e32 v35, v40
	v_exp_f32_e32 v38, v38
	v_exp_f32_e32 v39, v39
	v_pk_mul_f32 v[18:19], v[22:23], v[18:19]
	v_pk_mul_f32 v[28:29], v[34:35], v[28:29] op_sel_hi:[0,1]
	v_pk_mul_f32 v[30:31], v[34:35], v[30:31] op_sel_hi:[0,1]
	v_exp_f32_e32 v34, v28
	v_add_f32_e32 v28, 1.0, v35
	v_exp_f32_e32 v35, v41
	v_exp_f32_e32 v37, v29
	v_exp_f32_e32 v40, v31
	v_add_f32_e32 v31, 1.0, v39
	v_add_f32_e32 v29, 1.0, v35
	v_add_f32_e32 v35, 1.0, v37
	v_exp_f32_e32 v37, v30
	v_add_f32_e32 v30, 1.0, v38
	v_rcp_f32_e32 v28, v28
	v_add_f32_e32 v34, 1.0, v34
	v_rcp_f32_e32 v29, v29
	v_rcp_f32_e32 v30, v30
	v_add_f32_e32 v37, 1.0, v37
	v_rcp_f32_e32 v31, v31
	v_rcp_f32_e32 v34, v34
	v_rcp_f32_e32 v35, v35
	v_rcp_f32_e32 v38, v37
	v_add_f32_e32 v37, 1.0, v40
	v_rcp_f32_e32 v39, v37
	v_pk_mul_f32 v[16:17], v[20:21], v[16:17]
	v_pk_mul_f32 v[18:19], v[36:37], v[18:19] op_sel_hi:[0,1]
	v_pk_mul_f32 v[16:17], v[36:37], v[16:17] op_sel_hi:[0,1]
	v_lshl_add_u64 v[32:33], s[38:39], 0, v[148:149]
	v_pk_mul_f32 v[20:21], v[36:37], v[24:25] op_sel_hi:[0,1]
	v_pk_mul_f32 v[18:19], v[30:31], v[18:19]
	v_pk_mul_f32 v[16:17], v[28:29], v[16:17]
	v_lshl_add_u64 v[32:33], v[32:33], 0, v[208:209]
	v_pk_mul_f32 v[22:23], v[36:37], v[26:27] op_sel_hi:[0,1]
	v_pk_mul_f32 v[20:21], v[34:35], v[20:21]
	v_cvt_pk_bf16_f32 v16, v16, v17
	v_cvt_pk_bf16_f32 v17, v18, v19
	v_pk_mul_f32 v[22:23], v[38:39], v[22:23]
	v_cvt_pk_bf16_f32 v18, v20, v21
	v_pk_mul_f32 v[8:9], v[12:13], v[8:9]
	v_cvt_pk_bf16_f32 v19, v22, v23
	global_store_dwordx4 v[32:33], v[16:19], off nt
	v_pk_mul_f32 v[10:11], v[14:15], v[10:11]
	v_mul_f32_e32 v20, v161, v161
	v_mul_f32_e32 v18, 0xbfb8aa3b, v161
	v_pk_mul_f32 v[24:25], v[18:19], v[4:5] op_sel_hi:[0,1]
	v_pk_mul_f32 v[22:23], v[18:19], v[6:7] op_sel_hi:[0,1]
	v_exp_f32_e32 v19, v24
	v_exp_f32_e32 v22, v22
	v_exp_f32_e32 v23, v23
	v_pk_mul_f32 v[2:3], v[6:7], v[2:3]
	v_pk_mul_f32 v[12:13], v[18:19], v[12:13] op_sel_hi:[0,1]
	v_pk_mul_f32 v[14:15], v[18:19], v[14:15] op_sel_hi:[0,1]
	v_exp_f32_e32 v18, v12
	v_add_f32_e32 v12, 1.0, v19
	v_exp_f32_e32 v19, v25
	v_exp_f32_e32 v21, v13
	v_exp_f32_e32 v24, v15
	v_add_f32_e32 v15, 1.0, v23
	v_add_f32_e32 v13, 1.0, v19
	v_add_f32_e32 v19, 1.0, v21
	v_exp_f32_e32 v21, v14
	v_add_f32_e32 v14, 1.0, v22
	v_rcp_f32_e32 v12, v12
	v_add_f32_e32 v18, 1.0, v18
	v_add_f32_e32 v21, 1.0, v21
	v_rcp_f32_e32 v13, v13
	v_rcp_f32_e32 v14, v14
	v_rcp_f32_e32 v22, v21
	v_rcp_f32_e32 v15, v15
	v_add_f32_e32 v21, 1.0, v24
	v_rcp_f32_e32 v18, v18
	v_rcp_f32_e32 v19, v19
	v_rcp_f32_e32 v23, v21
	v_pk_mul_f32 v[0:1], v[4:5], v[0:1]
	v_lshl_add_u64 v[16:17], s[38:39], 0, v[150:151]
	v_pk_mul_f32 v[0:1], v[20:21], v[0:1] op_sel_hi:[0,1]
	v_pk_mul_f32 v[2:3], v[20:21], v[2:3] op_sel_hi:[0,1]
	v_lshl_add_u64 v[16:17], v[16:17], 0, v[208:209]
	v_pk_mul_f32 v[4:5], v[20:21], v[8:9] op_sel_hi:[0,1]
	v_pk_mul_f32 v[6:7], v[20:21], v[10:11] op_sel_hi:[0,1]
	v_pk_mul_f32 v[2:3], v[14:15], v[2:3]
	v_pk_mul_f32 v[0:1], v[12:13], v[0:1]
	s_andn2_b64 vcc, exec, s[36:37]
	s_mov_b64 s[2:3], -1
	v_pk_mul_f32 v[6:7], v[22:23], v[6:7]
	v_pk_mul_f32 v[4:5], v[18:19], v[4:5]
	v_cvt_pk_bf16_f32 v0, v0, v1
	v_cvt_pk_bf16_f32 v1, v2, v3
	s_nop 0
	v_cvt_pk_bf16_f32 v2, v4, v5
	v_cvt_pk_bf16_f32 v3, v6, v7
	global_store_dwordx4 v[16:17], v[0:3], off nt
	s_mov_b32 s98, 1
	s_cbranch_vccnz .LBB0_567
	s_andn2_b64 vcc, exec, s[22:23]
	s_cbranch_vccnz .LBB0_566
	s_barrier
	s_branch .LBB0_566
.Lgu_rlx0:
	s_waitcnt vmcnt(18)
	s_branch .Lgu_join0

	.amdhsa_kernel _Z6mk_fwd4Args
		.amdhsa_group_segment_fixed_size 0
		.amdhsa_private_segment_fixed_size 0
		.amdhsa_kernarg_size 416
		.amdhsa_user_sgpr_count 2
		.amdhsa_user_sgpr_dispatch_ptr 0
		.amdhsa_user_sgpr_queue_ptr 0
		.amdhsa_user_sgpr_kernarg_segment_ptr 1
		.amdhsa_user_sgpr_dispatch_id 0
		.amdhsa_user_sgpr_kernarg_preload_length 0
		.amdhsa_user_sgpr_kernarg_preload_offset 0
		.amdhsa_user_sgpr_private_segment_size 0
		.amdhsa_uses_dynamic_stack 0
		.amdhsa_enable_private_segment 0
		.amdhsa_system_sgpr_workgroup_id_x 1
		.amdhsa_system_sgpr_workgroup_id_y 0
		.amdhsa_system_sgpr_workgroup_id_z 0
		.amdhsa_system_sgpr_workgroup_info 0
		.amdhsa_system_vgpr_workitem_id 2
		.amdhsa_next_free_vgpr 255
		.amdhsa_next_free_sgpr 102
		.amdhsa_accum_offset 256
		.amdhsa_reserve_vcc 1
		.amdhsa_float_round_mode_32 0
		.amdhsa_float_round_mode_16_64 0
		.amdhsa_float_denorm_mode_32 3
		.amdhsa_float_denorm_mode_16_64 3
		.amdhsa_dx10_clamp 1
		.amdhsa_ieee_mode 1
		.amdhsa_fp16_overflow 0
		.amdhsa_tg_split 0
		.amdhsa_exception_fp_ieee_invalid_op 0
		.amdhsa_exception_fp_denorm_src 0
		.amdhsa_exception_fp_ieee_div_zero 0
		.amdhsa_exception_fp_ieee_overflow 0
		.amdhsa_exception_fp_ieee_underflow 0
		.amdhsa_exception_fp_ieee_inexact 0
		.amdhsa_exception_int_div_zero 0
	.end_amdhsa_kernel

amdhsa.kernels:
  - .agpr_count:     0
    .args:
      - .offset:         0
        .size:           160
        .value_kind:     by_value
      - .offset:         160
        .size:           4
        .value_kind:     hidden_block_count_x
      - .offset:         164
        .size:           4
        .value_kind:     hidden_block_count_y
      - .offset:         168
        .size:           4
        .value_kind:     hidden_block_count_z
      - .offset:         172
        .size:           2
        .value_kind:     hidden_group_size_x
      - .offset:         174
        .size:           2
        .value_kind:     hidden_group_size_y
      - .offset:         176
        .size:           2
        .value_kind:     hidden_group_size_z
      - .offset:         178
        .size:           2
        .value_kind:     hidden_remainder_x
      - .offset:         180
        .size:           2
        .value_kind:     hidden_remainder_y
      - .offset:         182
        .size:           2
        .value_kind:     hidden_remainder_z
      - .offset:         200
        .size:           8
        .value_kind:     hidden_global_offset_x
      - .offset:         208
        .size:           8
        .value_kind:     hidden_global_offset_y
      - .offset:         216
        .size:           8
        .value_kind:     hidden_global_offset_z
      - .offset:         224
        .size:           2
        .value_kind:     hidden_grid_dims
      - .offset:         248
        .size:           8
        .value_kind:     hidden_multigrid_sync_arg
      - .offset:         280
        .size:           4
        .value_kind:     hidden_dynamic_lds_size
    .group_segment_fixed_size: 0
    .kernarg_segment_align: 8
    .kernarg_segment_size: 416
    .language:       OpenCL C
    .language_version:
      - 2
      - 0
    .max_flat_workgroup_size: 512
    .name:           _Z6mk_fwd4Args
    .private_segment_fixed_size: 0
    .sgpr_count:     108
    .sgpr_spill_count: 126
    .symbol:         _Z6mk_fwd4Args.kd
    .uniform_work_group_size: 1
    .uses_dynamic_stack: false
    .vgpr_count:     255
    .vgpr_spill_count: 0
    .wavefront_size: 64
